# S5 scan loops: steady-state chunks 17..268 run in a trimmed loop body (single incrementing row pointer, no per-chunk row arithmetic, unmasked u since the B-bar operand is zero for k>=16)
# speedup vs baseline: 1.0421x; 1.0012x over previous
; #define LAS __attribute__((address_space(3)))
; DI void s5_phase(const KArgs& a, int zz, int o, const bf16_t* H, bf16_t* YF, bf16_t* YB, LAS unsigned char* lds, int G, int bid, int wave, int lane) {
;     ...
;         auto chunk_row = [&](int ci) -> size_t { const bool seg = ci < 16; const int k = seg ? ci : ci - 16, nch = seg ? 16 : 256, cidx = DIRC ? nch - 1 - k : k;
;             return seg ? (size_t)ML + b * TC + cidx * 16 : (size_t)b * T + cidx * 16; };
;     ...
;         auto loadu = [&](const int ci) __attribute__((always_inline)) -> u32x4 {
;             const int cc = ci < 272 ? ci : 271;
;             u32x4 r = *(const u32x4*)(Hg + (chunk_row(cc) + fr) * D);
;             const bool keep = fq < 2;
;             r.x = keep ? r.x : 0u; r.y = keep ? r.y : 0u; r.z = keep ? r.z : 0u; r.w = keep ? r.w : 0u;
;             return r; };
;         auto stageA = [&](const u32x4 uu) __attribute__((always_inline)) {
;             const bf16x8 Au = __builtin_bit_cast(bf16x8, uu);
; #pragma unroll
;             for (int nt = 0; nt < 8; ++nt) { const f32x4 acc = MFMA16(Bb[nt], Au, ((f32x4){0.f, 0.f, 0.f, 0.f}));
;                 *(LAS f32x4*)(BU + fr * 132 + 16 * nt + fq * 4) = acc; } };
;         u32x4 u1 = loadu(1), u2 = loadu(2);
;         stageA(loadu(0));
;         S5_CB();
;         size_t rowprev = 0;
;         auto iter = [&](const int ci, const bool do_c) __attribute__((always_inline)) {
;             const size_t row0 = chunk_row(ci);
;             const u32x4 u3 = loadu(ci + 3);
;             f32x2 bu[16];
; #pragma unroll
;             for (int s = 0; s < 16; ++s) { const int tt = DIRC ? 15 - s : s; bu[s] = *(const LAS f32x2*)(BU + tt * 132 + 2 * lane); }
;             bf16x8 Ax[4];
;             if (do_c) {
; #pragma unroll
;                 for (int kb = 0; kb < 4; ++kb) Ax[kb] = *(const LAS bf16x8*)(XS + fr * 68 + kb * 16 + fq * 4); }
;             S5_CB();
;             stageA(u1);
;             S5_CB();
; #pragma unroll
;             for (int s = 0; s < 16; ++s) { const int tt = DIRC ? 15 - s : s;
;                 const float nr = __builtin_fmaf(abr, xr, __builtin_fmaf(nabi, xi, bu[s][0])); const float ni = __builtin_fmaf(abr, xi, __builtin_fmaf(abi, xr, bu[s][1])); xr = nr; xi = ni;
;                 XS[tt * 68 + lane] = pk2(xr, xi); }
;             if (do_c) {
;                 f32x4 ya = (f32x4){0.f, 0.f, 0.f, 0.f};
; #pragma unroll
.LBB0_414:
	s_waitcnt vmcnt(1)
	v_cndmask_b32_e64 v173, 0, v52, s[38:39]
	v_sub_co_u32_e64 v52, s[26:27], s25, 16
	s_and_b64 s[30:31], s[26:27], exec
	v_readfirstlane_b32 s30, v52
	s_cselect_b32 s30, s25, s30
	s_cselect_b32 s31, 15, 0xff
	s_sub_i32 s30, s31, s30
	s_lshl_b32 s30, s30, 4
	s_ashr_i32 s31, s30, 31
	s_and_b64 s[26:27], s[26:27], exec
	s_cselect_b32 s26, s23, s58
	s_cselect_b32 s27, s24, s59
	s_add_u32 s26, s26, s30
	s_addc_u32 s27, s27, s31
	s_min_i32 s36, s25, 0x10c
	s_cmp_lt_u32 s25, 13
	s_cselect_b64 s[30:31], -1, 0
	s_and_b64 s[34:35], s[30:31], exec
	s_cselect_b32 s34, -3, 13
	s_cselect_b32 s35, 15, 0xff
	s_sub_i32 s34, s34, s36
	s_add_i32 s34, s34, s35
	s_lshl_b32 s34, s34, 4
	s_ashr_i32 s35, s34, 31
	s_and_b64 s[30:31], s[30:31], exec
	s_cselect_b32 s31, s23, s58
	s_cselect_b32 s30, s24, s59
	s_add_u32 s31, s31, s34
	s_addc_u32 s30, s30, s35
	v_mfma_f32_16x16x32_bf16 v[174:177], v[24:27], v[48:51], 0
	v_cndmask_b32_e64 v172, 0, v53, s[38:39]
	v_mov_b32_e32 v53, s30
	v_or_b32_e32 v52, s31, v104
	v_lshlrev_b64 v[52:53], 11, v[52:53]
	v_lshl_add_u64 v[52:53], v[126:127], 0, v[52:53]
	v_add_u32_e32 v148, v134, v107
	v_cndmask_b32_e64 v170, 0, v55, s[38:39]
	v_cndmask_b32_e64 v171, 0, v54, s[38:39]
	global_load_dwordx4 v[52:55], v[52:53], off
	ds_read_b128 v[56:59], v148 offset:8448
	ds_read_b128 v[60:63], v148 offset:8512
	ds_read_b128 v[64:67], v148 offset:8576
	ds_read_b128 v[68:71], v148 offset:8640
	ds_read_b64 v[100:101], v159 offset:1248
	ds_read_b64 v[102:103], v159 offset:1776
	ds_read_b64 v[96:97], v159 offset:192
	ds_read_b64 v[98:99], v159 offset:720
	ds_read_b64 v[92:93], v160 offset:1184
	ds_read_b64 v[94:95], v160 offset:1712
	ds_read_b64 v[88:89], v160 offset:128
	ds_read_b64 v[90:91], v160 offset:656
	ds_read_b64 v[84:85], v161 offset:1120
	ds_read_b64 v[86:87], v161 offset:1648
	ds_read_b64 v[80:81], v161 offset:64
	ds_read_b64 v[82:83], v161 offset:592
	ds_read_b64 v[76:77], v117 offset:1056
	ds_read_b64 v[78:79], v117 offset:1584
	ds_read_b64 v[72:73], v117
	ds_read_b64 v[74:75], v117 offset:528
	ds_write_b128 v157, v[174:177]
	v_mfma_f32_16x16x32_bf16 v[174:177], v[20:23], v[48:51], 0
	s_waitcnt lgkmcnt(15)
	v_mfma_f32_16x16x32_bf16 v[56:59], v[32:35], v[56:59], 0
	v_mfma_f32_16x16x32_bf16 v[56:59], v[36:39], v[60:63], v[56:59]
	v_mfma_f32_16x16x32_bf16 v[56:59], v[40:43], v[64:67], v[56:59]
	v_mfma_f32_16x16x32_bf16 v[56:59], v[44:47], v[68:71], v[56:59]
	s_waitcnt lgkmcnt(15)
	v_fma_f32 v60, -v125, v133, v102
	v_fma_f32 v61, v125, v132, v103
	v_fmac_f32_e32 v60, v122, v132
	v_fmac_f32_e32 v61, v122, v133
	v_fma_f32 v63, -v125, v61, v100
	v_fmac_f32_e32 v101, v125, v60
	v_fmac_f32_e32 v63, v122, v60
	v_fmac_f32_e32 v101, v122, v61
	v_cvt_pk_bf16_f32 v62, v60, v61
	v_cvt_pk_bf16_f32 v60, v63, v101
	ds_write2_b32 v162, v60, v62 offset0:120 offset1:188
	ds_write_b128 v157, v[174:177] offset:64
	v_mfma_f32_16x16x32_bf16 v[174:177], v[16:19], v[48:51], 0
	s_waitcnt lgkmcnt(15)
	v_fma_f32 v60, -v125, v101, v98
	v_fma_f32 v61, v125, v63, v99
	v_fmac_f32_e32 v60, v122, v63
	v_fmac_f32_e32 v61, v122, v101
	v_fma_f32 v63, -v125, v61, v96
	v_fmac_f32_e32 v97, v125, v60
	v_fmac_f32_e32 v63, v122, v60
	v_fmac_f32_e32 v97, v122, v61
	v_cvt_pk_bf16_f32 v62, v60, v61
	v_cvt_pk_bf16_f32 v60, v63, v97
	ds_write2_b32 v163, v60, v62 offset0:112 offset1:180
	ds_write_b128 v157, v[174:177] offset:128
	v_mfma_f32_16x16x32_bf16 v[174:177], v[12:15], v[48:51], 0
	s_waitcnt lgkmcnt(15)
	v_fma_f32 v60, -v125, v97, v94
	v_fma_f32 v61, v125, v63, v95
	v_fmac_f32_e32 v60, v122, v63
	v_fmac_f32_e32 v61, v122, v97
	v_fma_f32 v63, -v125, v61, v92
	v_fmac_f32_e32 v93, v125, v60
	v_fmac_f32_e32 v63, v122, v60
	v_fmac_f32_e32 v93, v122, v61
	v_cvt_pk_bf16_f32 v62, v60, v61
	v_cvt_pk_bf16_f32 v60, v63, v93
	ds_write2_b32 v164, v60, v62 offset0:104 offset1:172
	ds_write_b128 v157, v[174:177] offset:192
	v_mfma_f32_16x16x32_bf16 v[174:177], v[8:11], v[48:51], 0
	s_waitcnt lgkmcnt(15)
	v_fma_f32 v60, -v125, v93, v90
	v_fma_f32 v61, v125, v63, v91
	v_fmac_f32_e32 v60, v122, v63
	v_fmac_f32_e32 v61, v122, v93
	v_fma_f32 v63, -v125, v61, v88
	v_fmac_f32_e32 v89, v125, v60
	v_fmac_f32_e32 v63, v122, v60
	v_fmac_f32_e32 v89, v122, v61
	v_cvt_pk_bf16_f32 v62, v60, v61
	v_cvt_pk_bf16_f32 v60, v63, v89
	ds_write2_b32 v165, v60, v62 offset0:96 offset1:164
	ds_write_b128 v157, v[174:177] offset:256
	v_mfma_f32_16x16x32_bf16 v[174:177], v[4:7], v[48:51], 0
	s_waitcnt lgkmcnt(15)
	v_fma_f32 v60, -v125, v89, v86
	v_fma_f32 v61, v125, v63, v87
	v_fmac_f32_e32 v60, v122, v63
	v_fmac_f32_e32 v61, v122, v89
	v_fma_f32 v63, -v125, v61, v84
	v_fmac_f32_e32 v85, v125, v60
	v_fmac_f32_e32 v63, v122, v60
	v_fmac_f32_e32 v85, v122, v61
	v_cvt_pk_bf16_f32 v62, v60, v61
	v_cvt_pk_bf16_f32 v60, v63, v85
	ds_write2_b32 v166, v60, v62 offset0:88 offset1:156
	ds_write_b128 v157, v[174:177] offset:320
	v_mfma_f32_16x16x32_bf16 v[174:177], v[0:3], v[48:51], 0
	s_waitcnt lgkmcnt(15)
	v_fma_f32 v60, -v125, v85, v82
	v_fma_f32 v61, v125, v63, v83
	v_fmac_f32_e32 v60, v122, v63
	v_fmac_f32_e32 v61, v122, v85
	v_fma_f32 v63, -v125, v61, v80
	v_fmac_f32_e32 v81, v125, v60
	v_fmac_f32_e32 v63, v122, v60
	v_fmac_f32_e32 v81, v122, v61
	v_cvt_pk_bf16_f32 v62, v60, v61
	v_cvt_pk_bf16_f32 v60, v63, v81
	ds_write2_b32 v167, v60, v62 offset0:80 offset1:148
	ds_write_b128 v157, v[174:177] offset:384
	v_mfma_f32_16x16x32_bf16 v[174:177], v[28:31], v[48:51], 0
	s_waitcnt lgkmcnt(15)
	v_fma_f32 v60, -v125, v81, v78
	v_fma_f32 v61, v125, v63, v79
	v_fmac_f32_e32 v60, v122, v63
	v_fmac_f32_e32 v61, v122, v81
	v_fma_f32 v63, -v125, v61, v76
	v_fmac_f32_e32 v77, v125, v60
	v_fmac_f32_e32 v63, v122, v60
	v_fmac_f32_e32 v77, v122, v61
	v_cvt_pk_bf16_f32 v62, v60, v61
	v_cvt_pk_bf16_f32 v60, v63, v77
	ds_write2_b32 v168, v60, v62 offset0:72 offset1:140
	ds_write_b128 v157, v[174:177] offset:448
	s_waitcnt lgkmcnt(15)
	v_fma_f32 v61, -v125, v77, v74
	v_fma_f32 v60, v125, v63, v75
	v_fmac_f32_e32 v61, v122, v63
	v_fmac_f32_e32 v60, v122, v77
	v_pk_fma_f32 v[62:63], v[124:125], v[60:61], v[72:73]
	v_mov_b32_e32 v72, v61
	v_mov_b32_e32 v73, v60
	v_pk_fma_f32 v[132:133], v[122:123], v[72:73], v[62:63]
	v_cvt_pk_bf16_f32 v74, v61, v60
	v_cvt_pk_bf16_f32 v60, v132, v133
	ds_write2_b32 v169, v60, v74 offset0:64 offset1:132
	v_cvt_pk_bf16_f32 v56, v56, v57
	v_cvt_pk_bf16_f32 v57, v58, v59
	v_lshl_add_u64 v[62:63], s[0:1], 0, v[104:105]
	v_lshlrev_b64 v[62:63], 11, v[62:63]
	v_lshl_add_u64 v[62:63], v[128:129], 0, v[62:63]
	global_store_dwordx2 v[62:63], v[56:57], off
	s_mov_b64 s[0:1], s[26:27]
	v_mov_b32_e32 v48, v173
	v_mov_b32_e32 v49, v172
	v_mov_b32_e32 v50, v171
	v_mov_b32_e32 v51, v170
	s_add_i32 s25, s25, 1
	s_cmp_eq_u32 s25, 17
	s_cbranch_scc1 .Ls5f_bwd_entry
; #define LAS __attribute__((address_space(3)))
; DI unsigned pk2(float lo, float hi) { f32x2 v = {lo, hi}; bf16x2_t b = __builtin_convertvector(v, bf16x2_t); return __builtin_bit_cast(unsigned, b); }
; #define MFMA16(a, b, c) __builtin_amdgcn_mfma_f32_16x16x32_bf16((a), (b), (c), 0, 0, 0)
; DI void s5_phase(const KArgs& a, int zz, int o, const bf16_t* H, bf16_t* YF, bf16_t* YB, LAS unsigned char* lds, int G, int bid, int wave, int lane) {
;     ...
;         auto chunk_row = [&](int ci) -> size_t { const bool seg = ci < 16; const int k = seg ? ci : ci - 16, nch = seg ? 16 : 256, cidx = DIRC ? nch - 1 - k : k;
;             return seg ? (size_t)ML + b * TC + cidx * 16 : (size_t)b * T + cidx * 16; };
;     ...
;         {
;             f32x4 ya = (f32x4){0.f, 0.f, 0.f, 0.f};
; #pragma unroll
;             for (int kb = 0; kb < 4; ++kb) { const bf16x8 Ax = *(const LAS bf16x8*)(XS + fr * 68 + kb * 16 + fq * 4); ya = MFMA16(Cb[kb], Ax, ya); }
;             u32x2 w; w.x = pk2(ya[0], ya[1]); w.y = pk2(ya[2], ya[3]); *(u32x2*)(Y + (rowprev + fr) * D + g * 16 + fq * 4) = w;
;         }
	s_cmpk_lg_i32 s25, 0x110
	s_cbranch_scc1 .LBB0_414
	s_waitcnt vmcnt(0)
	ds_read_b128 v[48:51], v148 offset:8448
	ds_read_b128 v[52:55], v148 offset:8512
	s_mov_b32 s36, s12
	s_waitcnt lgkmcnt(1)
	v_mfma_f32_16x16x32_bf16 v[48:51], v[32:35], v[48:51], 0
	s_waitcnt lgkmcnt(0)
	v_mfma_f32_16x16x32_bf16 v[48:51], v[36:39], v[52:55], v[48:51]
	ds_read_b128 v[52:55], v148 offset:8576
	s_waitcnt lgkmcnt(0)
	v_mfma_f32_16x16x32_bf16 v[48:51], v[40:43], v[52:55], v[48:51]
	ds_read_b128 v[52:55], v148 offset:8640
	v_lshlrev_b32_e32 v148, 1, v106
	s_waitcnt lgkmcnt(0)
	v_mfma_f32_16x16x32_bf16 v[48:51], v[44:47], v[52:55], v[48:51]
	s_nop 7
	v_cvt_pk_bf16_f32 v48, v48, v49
	v_cvt_pk_bf16_f32 v49, v50, v51
	v_mov_b32_e32 v51, s27
	v_or_b32_e32 v50, s26, v104
	v_lshlrev_b64 v[50:51], 11, v[50:51]
	v_lshl_add_u64 v[50:51], s[6:7], 0, v[50:51]
	v_lshl_add_u64 v[50:51], s[52:53], 1, v[50:51]
	v_lshl_add_u64 v[50:51], v[50:51], 0, v[148:149]
	global_store_dwordx2 v[50:51], v[48:49], off
	s_waitcnt lgkmcnt(0)
	s_branch .LBB0_394
.Ls5f_bwd_entry:
	s_add_u32 s98, s58, 0xfb0
	s_addc_u32 s99, s59, 0
	s_mov_b32 s100, 0x20000
	s_mov_b32 s101, 0
	s_lshl_b64 s[98:99], s[98:99], 11
	v_lshlrev_b64 v[182:183], 11, v[104:105]
	v_lshl_add_u64 v[178:179], v[126:127], 0, v[182:183]
	v_lshl_add_u64 v[180:181], v[128:129], 0, v[182:183]
	v_lshl_add_u64 v[180:181], v[180:181], 0, s[100:101]
	s_mov_b32 s100, 17
; #define LAS __attribute__((address_space(3)))
; DI unsigned pk2(float lo, float hi) { f32x2 v = {lo, hi}; bf16x2_t b = __builtin_convertvector(v, bf16x2_t); return __builtin_bit_cast(unsigned, b); }
; #define MFMA16(a, b, c) __builtin_amdgcn_mfma_f32_16x16x32_bf16((a), (b), (c), 0, 0, 0)
; #define S5_CB() asm volatile("" ::: "memory")
; DI void s5_phase(const KArgs& a, int zz, int o, const bf16_t* H, bf16_t* YF, bf16_t* YB, LAS unsigned char* lds, int G, int bid, int wave, int lane) {
;     ...
;         auto iter = [&](const int ci, const bool do_c) __attribute__((always_inline)) {
;             const size_t row0 = chunk_row(ci);
;             const u32x4 u3 = loadu(ci + 3);
;             f32x2 bu[16];
; #pragma unroll
;             for (int s = 0; s < 16; ++s) { const int tt = DIRC ? 15 - s : s; bu[s] = *(const LAS f32x2*)(BU + tt * 132 + 2 * lane); }
;             bf16x8 Ax[4];
;             if (do_c) {
; #pragma unroll
;                 for (int kb = 0; kb < 4; ++kb) Ax[kb] = *(const LAS bf16x8*)(XS + fr * 68 + kb * 16 + fq * 4); }
;             S5_CB();
;             stageA(u1);
;             S5_CB();
; #pragma unroll
;             for (int s = 0; s < 16; ++s) { const int tt = DIRC ? 15 - s : s;
;                 const float nr = __builtin_fmaf(abr, xr, __builtin_fmaf(nabi, xi, bu[s][0])); const float ni = __builtin_fmaf(abr, xi, __builtin_fmaf(abi, xr, bu[s][1])); xr = nr; xi = ni;
;                 XS[tt * 68 + lane] = pk2(xr, xi); }
;             if (do_c) {
;                 f32x4 ya = (f32x4){0.f, 0.f, 0.f, 0.f};
; #pragma unroll
;                 for (int kb = 0; kb < 4; ++kb) ya = MFMA16(Cb[kb], Ax[kb], ya);
;                 u32x2 w; w.x = pk2(ya[0], ya[1]); w.y = pk2(ya[2], ya[3]); *(u32x2*)(Y + (rowprev + fr) * D + g * 16 + fq * 4) = w; }
;             S5_CB();
;             rowprev = row0; u1 = u2; u2 = u3;
;         };
;         iter(0, false);
;         for (int ci = 1; ci < 272; ++ci) iter(ci, true);
.Ls5f_bwd_loop:
	v_mfma_f32_16x16x32_bf16 v[174:177], v[24:27], v[48:51], 0
	ds_read_b128 v[56:59], v148 offset:8448
	ds_read_b128 v[60:63], v148 offset:8512
	ds_read_b128 v[64:67], v148 offset:8576
	ds_read_b128 v[68:71], v148 offset:8640
	ds_read_b64 v[100:101], v159 offset:1248
	ds_read_b64 v[102:103], v159 offset:1776
	ds_read_b64 v[96:97], v159 offset:192
	ds_read_b64 v[98:99], v159 offset:720
	ds_read_b64 v[92:93], v160 offset:1184
	ds_read_b64 v[94:95], v160 offset:1712
	ds_read_b64 v[88:89], v160 offset:128
	ds_read_b64 v[90:91], v160 offset:656
	ds_read_b64 v[84:85], v161 offset:1120
	ds_read_b64 v[86:87], v161 offset:1648
	ds_read_b64 v[80:81], v161 offset:64
	ds_read_b64 v[82:83], v161 offset:592
	ds_read_b64 v[76:77], v117 offset:1056
	ds_read_b64 v[78:79], v117 offset:1584
	ds_read_b64 v[72:73], v117
	ds_read_b64 v[74:75], v117 offset:528
	ds_write_b128 v157, v[174:177]
	v_mfma_f32_16x16x32_bf16 v[174:177], v[20:23], v[48:51], 0
	s_waitcnt lgkmcnt(15)
	v_mfma_f32_16x16x32_bf16 v[56:59], v[32:35], v[56:59], 0
	v_mfma_f32_16x16x32_bf16 v[56:59], v[36:39], v[60:63], v[56:59]
	v_mfma_f32_16x16x32_bf16 v[56:59], v[40:43], v[64:67], v[56:59]
	v_mfma_f32_16x16x32_bf16 v[56:59], v[44:47], v[68:71], v[56:59]
	v_fma_f32 v60, -v125, v133, v102
	v_fma_f32 v61, v125, v132, v103
	v_fmac_f32_e32 v60, v122, v132
	v_fmac_f32_e32 v61, v122, v133
	v_fma_f32 v63, -v125, v61, v100
	v_fmac_f32_e32 v101, v125, v60
	v_fmac_f32_e32 v63, v122, v60
	v_fmac_f32_e32 v101, v122, v61
	v_cvt_pk_bf16_f32 v62, v60, v61
	v_cvt_pk_bf16_f32 v60, v63, v101
	ds_write2_b32 v162, v60, v62 offset0:120 offset1:188
	ds_write_b128 v157, v[174:177] offset:64
	v_mfma_f32_16x16x32_bf16 v[174:177], v[16:19], v[48:51], 0
	s_waitcnt lgkmcnt(15)
	v_fma_f32 v60, -v125, v101, v98
	v_fma_f32 v61, v125, v63, v99
	v_fmac_f32_e32 v60, v122, v63
	v_fmac_f32_e32 v61, v122, v101
	v_fma_f32 v63, -v125, v61, v96
	v_fmac_f32_e32 v97, v125, v60
	v_fmac_f32_e32 v63, v122, v60
	v_fmac_f32_e32 v97, v122, v61
	v_cvt_pk_bf16_f32 v62, v60, v61
	v_cvt_pk_bf16_f32 v60, v63, v97
	ds_write2_b32 v163, v60, v62 offset0:112 offset1:180
	ds_write_b128 v157, v[174:177] offset:128
	v_mfma_f32_16x16x32_bf16 v[174:177], v[12:15], v[48:51], 0
	s_waitcnt lgkmcnt(15)
	v_fma_f32 v60, -v125, v97, v94
	v_fma_f32 v61, v125, v63, v95
	v_fmac_f32_e32 v60, v122, v63
	v_fmac_f32_e32 v61, v122, v97
	v_fma_f32 v63, -v125, v61, v92
	v_fmac_f32_e32 v93, v125, v60
	v_fmac_f32_e32 v63, v122, v60
	v_fmac_f32_e32 v93, v122, v61
	v_cvt_pk_bf16_f32 v62, v60, v61
	v_cvt_pk_bf16_f32 v60, v63, v93
	ds_write2_b32 v164, v60, v62 offset0:104 offset1:172
	ds_write_b128 v157, v[174:177] offset:192
	v_mfma_f32_16x16x32_bf16 v[174:177], v[8:11], v[48:51], 0
	s_waitcnt lgkmcnt(15)
	v_fma_f32 v60, -v125, v93, v90
	v_fma_f32 v61, v125, v63, v91
	v_fmac_f32_e32 v60, v122, v63
	v_fmac_f32_e32 v61, v122, v93
	v_fma_f32 v63, -v125, v61, v88
	v_fmac_f32_e32 v89, v125, v60
	v_fmac_f32_e32 v63, v122, v60
	v_fmac_f32_e32 v89, v122, v61
	v_cvt_pk_bf16_f32 v62, v60, v61
	v_cvt_pk_bf16_f32 v60, v63, v89
	ds_write2_b32 v165, v60, v62 offset0:96 offset1:164
	ds_write_b128 v157, v[174:177] offset:256
	v_mfma_f32_16x16x32_bf16 v[174:177], v[4:7], v[48:51], 0
	s_waitcnt lgkmcnt(15)
	v_fma_f32 v60, -v125, v89, v86
	v_fma_f32 v61, v125, v63, v87
	v_fmac_f32_e32 v60, v122, v63
	v_fmac_f32_e32 v61, v122, v89
	v_fma_f32 v63, -v125, v61, v84
	v_fmac_f32_e32 v85, v125, v60
	v_fmac_f32_e32 v63, v122, v60
	v_fmac_f32_e32 v85, v122, v61
	v_cvt_pk_bf16_f32 v62, v60, v61
	v_cvt_pk_bf16_f32 v60, v63, v85
	ds_write2_b32 v166, v60, v62 offset0:88 offset1:156
	ds_write_b128 v157, v[174:177] offset:320
	v_mfma_f32_16x16x32_bf16 v[174:177], v[0:3], v[48:51], 0
	s_waitcnt lgkmcnt(15)
	v_fma_f32 v60, -v125, v85, v82
	v_fma_f32 v61, v125, v63, v83
	v_fmac_f32_e32 v60, v122, v63
	v_fmac_f32_e32 v61, v122, v85
	v_fma_f32 v63, -v125, v61, v80
	v_fmac_f32_e32 v81, v125, v60
	v_fmac_f32_e32 v63, v122, v60
	v_fmac_f32_e32 v81, v122, v61
	v_cvt_pk_bf16_f32 v62, v60, v61
	v_cvt_pk_bf16_f32 v60, v63, v81
	ds_write2_b32 v167, v60, v62 offset0:80 offset1:148
	ds_write_b128 v157, v[174:177] offset:384
	v_mfma_f32_16x16x32_bf16 v[174:177], v[28:31], v[48:51], 0
	s_waitcnt lgkmcnt(15)
	v_fma_f32 v60, -v125, v81, v78
	v_fma_f32 v61, v125, v63, v79
	v_fmac_f32_e32 v60, v122, v63
	v_fmac_f32_e32 v61, v122, v81
	v_fma_f32 v63, -v125, v61, v76
	v_fmac_f32_e32 v77, v125, v60
	v_fmac_f32_e32 v63, v122, v60
	v_fmac_f32_e32 v77, v122, v61
	v_cvt_pk_bf16_f32 v62, v60, v61
	v_cvt_pk_bf16_f32 v60, v63, v77
	ds_write2_b32 v168, v60, v62 offset0:72 offset1:140
	ds_write_b128 v157, v[174:177] offset:448
	s_waitcnt lgkmcnt(15)
	v_fma_f32 v61, -v125, v77, v74
	v_fma_f32 v60, v125, v63, v75
	v_fmac_f32_e32 v61, v122, v63
	v_fmac_f32_e32 v60, v122, v77
	v_pk_fma_f32 v[62:63], v[124:125], v[60:61], v[72:73]
	v_mov_b32_e32 v72, v61
	v_mov_b32_e32 v73, v60
	v_pk_fma_f32 v[132:133], v[122:123], v[72:73], v[62:63]
	v_cvt_pk_bf16_f32 v74, v61, v60
	v_cvt_pk_bf16_f32 v60, v132, v133
	ds_write2_b32 v169, v60, v74 offset0:64 offset1:132
	v_cvt_pk_bf16_f32 v56, v56, v57
	v_cvt_pk_bf16_f32 v57, v58, v59
	v_lshl_add_u64 v[62:63], s[98:99], 0, v[180:181]
	global_store_dwordx2 v[62:63], v[56:57], off
	s_waitcnt vmcnt(1)
	v_mov_b32_e32 v48, v52
	v_mov_b32_e32 v49, v53
	v_mov_b32_e32 v50, v54
	v_mov_b32_e32 v51, v55
	v_lshl_add_u64 v[62:63], s[98:99], 0, v[178:179]
	global_load_dwordx4 v[52:55], v[62:63], off
	s_sub_u32 s98, s98, 0x8000
	s_subb_u32 s99, s99, 0
	s_add_i32 s100, s100, 1
	s_cmp_lg_u32 s100, 0x10d
	s_cbranch_scc1 .Ls5f_bwd_loop
	s_waitcnt vmcnt(0)
	s_mov_b32 s25, 0x10d
	s_add_u32 s0, s58, 48
	s_addc_u32 s1, s59, 0
	s_branch .LBB0_414

; #define LAS __attribute__((address_space(3)))
; DI void s5_phase(const KArgs& a, int zz, int o, const bf16_t* H, bf16_t* YF, bf16_t* YB, LAS unsigned char* lds, int G, int bid, int wave, int lane) {
;     ...
;         auto chunk_row = [&](int ci) -> size_t { const bool seg = ci < 16; const int k = seg ? ci : ci - 16, nch = seg ? 16 : 256, cidx = DIRC ? nch - 1 - k : k;
;             return seg ? (size_t)ML + b * TC + cidx * 16 : (size_t)b * T + cidx * 16; };
;     ...
;         auto loadu = [&](const int ci) __attribute__((always_inline)) -> u32x4 {
;             const int cc = ci < 272 ? ci : 271;
;             u32x4 r = *(const u32x4*)(Hg + (chunk_row(cc) + fr) * D);
;             const bool keep = fq < 2;
;             r.x = keep ? r.x : 0u; r.y = keep ? r.y : 0u; r.z = keep ? r.z : 0u; r.w = keep ? r.w : 0u;
;             return r; };
;         auto stageA = [&](const u32x4 uu) __attribute__((always_inline)) {
;             const bf16x8 Au = __builtin_bit_cast(bf16x8, uu);
; #pragma unroll
;             for (int nt = 0; nt < 8; ++nt) { const f32x4 acc = MFMA16(Bb[nt], Au, ((f32x4){0.f, 0.f, 0.f, 0.f}));
;                 *(LAS f32x4*)(BU + fr * 132 + 16 * nt + fq * 4) = acc; } };
;         u32x4 u1 = loadu(1), u2 = loadu(2);
;         stageA(loadu(0));
;         S5_CB();
;         size_t rowprev = 0;
;         auto iter = [&](const int ci, const bool do_c) __attribute__((always_inline)) {
;             const size_t row0 = chunk_row(ci);
;             const u32x4 u3 = loadu(ci + 3);
;             f32x2 bu[16];
; #pragma unroll
;             for (int s = 0; s < 16; ++s) { const int tt = DIRC ? 15 - s : s; bu[s] = *(const LAS f32x2*)(BU + tt * 132 + 2 * lane); }
;             bf16x8 Ax[4];
;             if (do_c) {
; #pragma unroll
;                 for (int kb = 0; kb < 4; ++kb) Ax[kb] = *(const LAS bf16x8*)(XS + fr * 68 + kb * 16 + fq * 4); }
;             S5_CB();
;             stageA(u1);
;             S5_CB();
; #pragma unroll
;             for (int s = 0; s < 16; ++s) { const int tt = DIRC ? 15 - s : s;
;                 const float nr = __builtin_fmaf(abr, xr, __builtin_fmaf(nabi, xi, bu[s][0])); const float ni = __builtin_fmaf(abr, xi, __builtin_fmaf(abi, xr, bu[s][1])); xr = nr; xi = ni;
;                 XS[tt * 68 + lane] = pk2(xr, xi); }
;             if (do_c) {
;                 f32x4 ya = (f32x4){0.f, 0.f, 0.f, 0.f};
; #pragma unroll
.LBB0_417:
	s_waitcnt vmcnt(1)
	s_cmp_lt_u32 s23, 16
	s_cselect_b64 s[26:27], -1, 0
	s_add_i32 s25, s24, 0xfffeff00
	s_and_b64 s[26:27], s[26:27], exec
	s_cselect_b32 s25, s24, s25
	s_cselect_b32 s26, s54, s56
	s_cselect_b32 s27, s55, s57
	s_add_u32 s26, s26, s25
	s_addc_u32 s27, s27, 0
	s_min_i32 s25, s23, 0x10c
	s_cmp_lt_u32 s23, 13
	s_cselect_b64 s[30:31], -1, 0
	s_lshl_b32 s25, s25, 4
	s_and_b64 s[30:31], s[30:31], exec
	s_movk_i32 s30, 0xff30
	s_cselect_b32 s30, 0x10030, s30
	s_cselect_b32 s31, s55, s57
	s_cselect_b32 s34, s54, s56
	s_add_i32 s25, s25, s30
	s_add_u32 s25, s34, s25
	s_addc_u32 s30, s31, 0
	v_mfma_f32_16x16x32_bf16 v[172:175], v[24:27], v[48:51], 0
	v_cndmask_b32_e64 v170, 0, v53, s[38:39]
	v_cndmask_b32_e64 v171, 0, v52, s[38:39]
	v_mov_b32_e32 v53, s30
	v_or_b32_e32 v52, s25, v104
	v_lshlrev_b64 v[52:53], 11, v[52:53]
	v_lshl_add_u64 v[52:53], v[126:127], 0, v[52:53]
	v_add_u32_e32 v132, v134, v107
	v_cndmask_b32_e64 v133, 0, v55, s[38:39]
	v_cndmask_b32_e64 v148, 0, v54, s[38:39]
	global_load_dwordx4 v[52:55], v[52:53], off
	ds_read_b128 v[56:59], v132 offset:8448
	ds_read_b128 v[60:63], v132 offset:8512
	ds_read_b128 v[64:67], v132 offset:8576
	ds_read_b128 v[68:71], v132 offset:8640
	ds_read_b64 v[100:101], v117
	ds_read_b64 v[102:103], v117 offset:528
	ds_read_b64 v[96:97], v117 offset:1056
	ds_read_b64 v[98:99], v117 offset:1584
	ds_read_b64 v[92:93], v161 offset:64
	ds_read_b64 v[94:95], v161 offset:592
	ds_read_b64 v[88:89], v161 offset:1120
	ds_read_b64 v[90:91], v161 offset:1648
	ds_read_b64 v[84:85], v160 offset:128
	ds_read_b64 v[86:87], v160 offset:656
	ds_read_b64 v[80:81], v160 offset:1184
	ds_read_b64 v[82:83], v160 offset:1712
	ds_read_b64 v[76:77], v159 offset:192
	ds_read_b64 v[78:79], v159 offset:720
	ds_read_b64 v[72:73], v159 offset:1248
	ds_read_b64 v[74:75], v159 offset:1776
	ds_write_b128 v157, v[172:175]
	v_mfma_f32_16x16x32_bf16 v[172:175], v[20:23], v[48:51], 0
	s_waitcnt lgkmcnt(15)
	v_mfma_f32_16x16x32_bf16 v[56:59], v[32:35], v[56:59], 0
	v_mfma_f32_16x16x32_bf16 v[56:59], v[36:39], v[60:63], v[56:59]
	v_mfma_f32_16x16x32_bf16 v[56:59], v[40:43], v[64:67], v[56:59]
	v_mfma_f32_16x16x32_bf16 v[56:59], v[44:47], v[68:71], v[56:59]
	s_waitcnt lgkmcnt(15)
	v_fma_f32 v60, -v125, v131, v100
	v_fma_f32 v61, v125, v130, v101
	v_fmac_f32_e32 v60, v122, v130
	v_fmac_f32_e32 v61, v122, v131
	v_fma_f32 v63, -v125, v61, v102
	v_fmac_f32_e32 v103, v125, v60
	v_fmac_f32_e32 v63, v122, v60
	v_fmac_f32_e32 v103, v122, v61
	v_cvt_pk_bf16_f32 v62, v60, v61
	v_cvt_pk_bf16_f32 v60, v63, v103
	ds_write2_b32 v169, v62, v60 offset0:64 offset1:132
	ds_write_b128 v157, v[172:175] offset:64
	v_mfma_f32_16x16x32_bf16 v[172:175], v[16:19], v[48:51], 0
	s_waitcnt lgkmcnt(15)
	v_fma_f32 v60, -v125, v103, v96
	v_fma_f32 v61, v125, v63, v97
	v_fmac_f32_e32 v60, v122, v63
	v_fmac_f32_e32 v61, v122, v103
	v_fma_f32 v63, -v125, v61, v98
	v_fmac_f32_e32 v99, v125, v60
	v_fmac_f32_e32 v63, v122, v60
	v_fmac_f32_e32 v99, v122, v61
	v_cvt_pk_bf16_f32 v62, v60, v61
	v_cvt_pk_bf16_f32 v60, v63, v99
	ds_write2_b32 v168, v62, v60 offset0:72 offset1:140
	ds_write_b128 v157, v[172:175] offset:128
	v_mfma_f32_16x16x32_bf16 v[172:175], v[12:15], v[48:51], 0
	s_waitcnt lgkmcnt(15)
	v_fma_f32 v60, -v125, v99, v92
	v_fma_f32 v61, v125, v63, v93
	v_fmac_f32_e32 v60, v122, v63
	v_fmac_f32_e32 v61, v122, v99
	v_fma_f32 v63, -v125, v61, v94
	v_fmac_f32_e32 v95, v125, v60
	v_fmac_f32_e32 v63, v122, v60
	v_fmac_f32_e32 v95, v122, v61
	v_cvt_pk_bf16_f32 v62, v60, v61
	v_cvt_pk_bf16_f32 v60, v63, v95
	ds_write2_b32 v167, v62, v60 offset0:80 offset1:148
	ds_write_b128 v157, v[172:175] offset:192
	v_mfma_f32_16x16x32_bf16 v[172:175], v[8:11], v[48:51], 0
	s_waitcnt lgkmcnt(15)
	v_fma_f32 v60, -v125, v95, v88
	v_fma_f32 v61, v125, v63, v89
	v_fmac_f32_e32 v60, v122, v63
	v_fmac_f32_e32 v61, v122, v95
	v_fma_f32 v63, -v125, v61, v90
	v_fmac_f32_e32 v91, v125, v60
	v_fmac_f32_e32 v63, v122, v60
	v_fmac_f32_e32 v91, v122, v61
	v_cvt_pk_bf16_f32 v62, v60, v61
	v_cvt_pk_bf16_f32 v60, v63, v91
	ds_write2_b32 v166, v62, v60 offset0:88 offset1:156
	ds_write_b128 v157, v[172:175] offset:256
	v_mfma_f32_16x16x32_bf16 v[172:175], v[4:7], v[48:51], 0
	s_waitcnt lgkmcnt(15)
	v_fma_f32 v60, -v125, v91, v84
	v_fma_f32 v61, v125, v63, v85
	v_fmac_f32_e32 v60, v122, v63
	v_fmac_f32_e32 v61, v122, v91
	v_fma_f32 v63, -v125, v61, v86
	v_fmac_f32_e32 v87, v125, v60
	v_fmac_f32_e32 v63, v122, v60
	v_fmac_f32_e32 v87, v122, v61
	v_cvt_pk_bf16_f32 v62, v60, v61
	v_cvt_pk_bf16_f32 v60, v63, v87
	ds_write2_b32 v165, v62, v60 offset0:96 offset1:164
	ds_write_b128 v157, v[172:175] offset:320
	v_mfma_f32_16x16x32_bf16 v[172:175], v[0:3], v[48:51], 0
	s_waitcnt lgkmcnt(15)
	v_fma_f32 v60, -v125, v87, v80
	v_fma_f32 v61, v125, v63, v81
	v_fmac_f32_e32 v60, v122, v63
	v_fmac_f32_e32 v61, v122, v87
	v_fma_f32 v63, -v125, v61, v82
	v_fmac_f32_e32 v83, v125, v60
	v_fmac_f32_e32 v63, v122, v60
	v_fmac_f32_e32 v83, v122, v61
	v_cvt_pk_bf16_f32 v62, v60, v61
	v_cvt_pk_bf16_f32 v60, v63, v83
	ds_write2_b32 v164, v62, v60 offset0:104 offset1:172
	ds_write_b128 v157, v[172:175] offset:384
	v_mfma_f32_16x16x32_bf16 v[172:175], v[28:31], v[48:51], 0
	s_waitcnt lgkmcnt(15)
	v_fma_f32 v60, -v125, v83, v76
	v_fma_f32 v61, v125, v63, v77
	v_fmac_f32_e32 v60, v122, v63
	v_fmac_f32_e32 v61, v122, v83
	v_fma_f32 v63, -v125, v61, v78
	v_fmac_f32_e32 v79, v125, v60
	v_fmac_f32_e32 v63, v122, v60
	v_fmac_f32_e32 v79, v122, v61
	v_cvt_pk_bf16_f32 v62, v60, v61
	v_cvt_pk_bf16_f32 v60, v63, v79
	ds_write2_b32 v163, v62, v60 offset0:112 offset1:180
	ds_write_b128 v157, v[172:175] offset:448
	s_waitcnt lgkmcnt(15)
	v_fma_f32 v61, -v125, v79, v72
	v_fma_f32 v60, v125, v63, v73
	v_fmac_f32_e32 v61, v122, v63
	v_fmac_f32_e32 v60, v122, v79
	v_pk_fma_f32 v[62:63], v[124:125], v[60:61], v[74:75]
	v_mov_b32_e32 v72, v61
	v_mov_b32_e32 v73, v60
	v_pk_fma_f32 v[130:131], v[122:123], v[72:73], v[62:63]
	v_cvt_pk_bf16_f32 v76, v61, v60
	v_cvt_pk_bf16_f32 v60, v130, v131
	ds_write2_b32 v162, v76, v60 offset0:120 offset1:188
	v_cvt_pk_bf16_f32 v56, v56, v57
	v_cvt_pk_bf16_f32 v57, v58, v59
	v_lshl_add_u64 v[62:63], s[0:1], 0, v[104:105]
	v_lshlrev_b64 v[62:63], 11, v[62:63]
	v_lshl_add_u64 v[62:63], v[128:129], 0, v[62:63]
	global_store_dwordx2 v[62:63], v[56:57], off
	s_mov_b64 s[0:1], s[26:27]
	v_mov_b32_e32 v48, v171
	v_mov_b32_e32 v49, v170
	v_mov_b32_e32 v50, v148
	v_mov_b32_e32 v51, v133
	s_add_i32 s23, s23, 1
	s_add_i32 s24, s24, 16
	s_cmp_eq_u32 s23, 17
	s_cbranch_scc1 .Ls5f_fwd_entry
; #define LAS __attribute__((address_space(3)))
; DI unsigned pk2(float lo, float hi) { f32x2 v = {lo, hi}; bf16x2_t b = __builtin_convertvector(v, bf16x2_t); return __builtin_bit_cast(unsigned, b); }
; #define MFMA16(a, b, c) __builtin_amdgcn_mfma_f32_16x16x32_bf16((a), (b), (c), 0, 0, 0)
; #define S5_CB() asm volatile("" ::: "memory")
; DI void s5_phase(const KArgs& a, int zz, int o, const bf16_t* H, bf16_t* YF, bf16_t* YB, LAS unsigned char* lds, int G, int bid, int wave, int lane) {
;     ...
;         auto iter = [&](const int ci, const bool do_c) __attribute__((always_inline)) {
;             const size_t row0 = chunk_row(ci);
;             const u32x4 u3 = loadu(ci + 3);
;             f32x2 bu[16];
; #pragma unroll
;             for (int s = 0; s < 16; ++s) { const int tt = DIRC ? 15 - s : s; bu[s] = *(const LAS f32x2*)(BU + tt * 132 + 2 * lane); }
;             bf16x8 Ax[4];
;             if (do_c) {
; #pragma unroll
;                 for (int kb = 0; kb < 4; ++kb) Ax[kb] = *(const LAS bf16x8*)(XS + fr * 68 + kb * 16 + fq * 4); }
;             S5_CB();
;             stageA(u1);
;             S5_CB();
; #pragma unroll
;             for (int s = 0; s < 16; ++s) { const int tt = DIRC ? 15 - s : s;
;                 const float nr = __builtin_fmaf(abr, xr, __builtin_fmaf(nabi, xi, bu[s][0])); const float ni = __builtin_fmaf(abr, xi, __builtin_fmaf(abi, xr, bu[s][1])); xr = nr; xi = ni;
;                 XS[tt * 68 + lane] = pk2(xr, xi); }
;             if (do_c) {
;                 f32x4 ya = (f32x4){0.f, 0.f, 0.f, 0.f};
; #pragma unroll
;                 for (int kb = 0; kb < 4; ++kb) ya = MFMA16(Cb[kb], Ax[kb], ya);
;                 u32x2 w; w.x = pk2(ya[0], ya[1]); w.y = pk2(ya[2], ya[3]); *(u32x2*)(Y + (rowprev + fr) * D + g * 16 + fq * 4) = w; }
;             S5_CB();
;             rowprev = row0; u1 = u2; u2 = u3;
;         };
;         iter(0, false);
;         for (int ci = 1; ci < 272; ++ci) iter(ci, true);
;         {
;             f32x4 ya = (f32x4){0.f, 0.f, 0.f, 0.f};
; #pragma unroll
;             for (int kb = 0; kb < 4; ++kb) { const bf16x8 Ax = *(const LAS bf16x8*)(XS + fr * 68 + kb * 16 + fq * 4); ya = MFMA16(Cb[kb], Ax, ya); }
;             u32x2 w; w.x = pk2(ya[0], ya[1]); w.y = pk2(ya[2], ya[3]); *(u32x2*)(Y + (rowprev + fr) * D + g * 16 + fq * 4) = w;
;         }
	s_cmp_lg_u32 s24, 0x11100
	s_cbranch_scc1 .LBB0_417
	s_waitcnt vmcnt(0)
	ds_read_b128 v[0:3], v132 offset:8448
	ds_read_b128 v[4:7], v132 offset:8512
	v_lshlrev_b32_e32 v148, 1, v106
	s_waitcnt lgkmcnt(1)
	v_mfma_f32_16x16x32_bf16 v[0:3], v[32:35], v[0:3], 0
	s_waitcnt lgkmcnt(0)
	v_mfma_f32_16x16x32_bf16 v[0:3], v[36:39], v[4:7], v[0:3]
	ds_read_b128 v[4:7], v132 offset:8576
	s_waitcnt lgkmcnt(0)
	v_mfma_f32_16x16x32_bf16 v[0:3], v[40:43], v[4:7], v[0:3]
	ds_read_b128 v[4:7], v132 offset:8640
	s_waitcnt lgkmcnt(0)
	v_mfma_f32_16x16x32_bf16 v[0:3], v[44:47], v[4:7], v[0:3]
	s_nop 7
	v_cvt_pk_bf16_f32 v0, v0, v1
	v_cvt_pk_bf16_f32 v1, v2, v3
	v_mov_b32_e32 v3, s27
	v_or_b32_e32 v2, s26, v104
	v_lshlrev_b64 v[2:3], 11, v[2:3]
	v_lshl_add_u64 v[2:3], s[4:5], 0, v[2:3]
	v_lshl_add_u64 v[2:3], s[52:53], 1, v[2:3]
	v_lshl_add_u64 v[2:3], v[2:3], 0, v[148:149]
	global_store_dwordx2 v[2:3], v[0:1], off
	s_waitcnt lgkmcnt(0)
	s_branch .LBB0_394
.Ls5f_fwd_entry:
	s_add_u32 s98, s56, 64
	s_addc_u32 s99, s57, 0
	s_mov_b32 s100, 0xfffe0000
	s_mov_b32 s101, -1
	s_lshl_b64 s[98:99], s[98:99], 11
	v_lshlrev_b64 v[182:183], 11, v[104:105]
	v_lshl_add_u64 v[178:179], v[126:127], 0, v[182:183]
	v_lshl_add_u64 v[180:181], v[128:129], 0, v[182:183]
	v_lshl_add_u64 v[180:181], v[180:181], 0, s[100:101]
	s_mov_b32 s100, 17
.Ls5f_fwd_loop:
	v_mfma_f32_16x16x32_bf16 v[172:175], v[24:27], v[48:51], 0
	ds_read_b128 v[56:59], v132 offset:8448
	ds_read_b128 v[60:63], v132 offset:8512
	ds_read_b128 v[64:67], v132 offset:8576
	ds_read_b128 v[68:71], v132 offset:8640
	ds_read_b64 v[100:101], v117
	ds_read_b64 v[102:103], v117 offset:528
	ds_read_b64 v[96:97], v117 offset:1056
	ds_read_b64 v[98:99], v117 offset:1584
	ds_read_b64 v[92:93], v161 offset:64
	ds_read_b64 v[94:95], v161 offset:592
	ds_read_b64 v[88:89], v161 offset:1120
	ds_read_b64 v[90:91], v161 offset:1648
	ds_read_b64 v[84:85], v160 offset:128
	ds_read_b64 v[86:87], v160 offset:656
	ds_read_b64 v[80:81], v160 offset:1184
	ds_read_b64 v[82:83], v160 offset:1712
	ds_read_b64 v[76:77], v159 offset:192
	ds_read_b64 v[78:79], v159 offset:720
	ds_read_b64 v[72:73], v159 offset:1248
	ds_read_b64 v[74:75], v159 offset:1776
	ds_write_b128 v157, v[172:175]
	v_mfma_f32_16x16x32_bf16 v[172:175], v[20:23], v[48:51], 0
	s_waitcnt lgkmcnt(15)
	v_mfma_f32_16x16x32_bf16 v[56:59], v[32:35], v[56:59], 0
	v_mfma_f32_16x16x32_bf16 v[56:59], v[36:39], v[60:63], v[56:59]
	v_mfma_f32_16x16x32_bf16 v[56:59], v[40:43], v[64:67], v[56:59]
	v_mfma_f32_16x16x32_bf16 v[56:59], v[44:47], v[68:71], v[56:59]
	v_fma_f32 v60, -v125, v131, v100
	v_fma_f32 v61, v125, v130, v101
	v_fmac_f32_e32 v60, v122, v130
	v_fmac_f32_e32 v61, v122, v131
	v_fma_f32 v63, -v125, v61, v102
	v_fmac_f32_e32 v103, v125, v60
	v_fmac_f32_e32 v63, v122, v60
	v_fmac_f32_e32 v103, v122, v61
	v_cvt_pk_bf16_f32 v62, v60, v61
	v_cvt_pk_bf16_f32 v60, v63, v103
	ds_write2_b32 v169, v62, v60 offset0:64 offset1:132
	ds_write_b128 v157, v[172:175] offset:64
	v_mfma_f32_16x16x32_bf16 v[172:175], v[16:19], v[48:51], 0
	s_waitcnt lgkmcnt(15)
	v_fma_f32 v60, -v125, v103, v96
	v_fma_f32 v61, v125, v63, v97
	v_fmac_f32_e32 v60, v122, v63
	v_fmac_f32_e32 v61, v122, v103
	v_fma_f32 v63, -v125, v61, v98
	v_fmac_f32_e32 v99, v125, v60
	v_fmac_f32_e32 v63, v122, v60
	v_fmac_f32_e32 v99, v122, v61
	v_cvt_pk_bf16_f32 v62, v60, v61
	v_cvt_pk_bf16_f32 v60, v63, v99
	ds_write2_b32 v168, v62, v60 offset0:72 offset1:140
	ds_write_b128 v157, v[172:175] offset:128
	v_mfma_f32_16x16x32_bf16 v[172:175], v[12:15], v[48:51], 0
	s_waitcnt lgkmcnt(15)
	v_fma_f32 v60, -v125, v99, v92
	v_fma_f32 v61, v125, v63, v93
	v_fmac_f32_e32 v60, v122, v63
	v_fmac_f32_e32 v61, v122, v99
	v_fma_f32 v63, -v125, v61, v94
	v_fmac_f32_e32 v95, v125, v60
	v_fmac_f32_e32 v63, v122, v60
	v_fmac_f32_e32 v95, v122, v61
	v_cvt_pk_bf16_f32 v62, v60, v61
	v_cvt_pk_bf16_f32 v60, v63, v95
	ds_write2_b32 v167, v62, v60 offset0:80 offset1:148
	ds_write_b128 v157, v[172:175] offset:192
	v_mfma_f32_16x16x32_bf16 v[172:175], v[8:11], v[48:51], 0
	s_waitcnt lgkmcnt(15)
	v_fma_f32 v60, -v125, v95, v88
	v_fma_f32 v61, v125, v63, v89
	v_fmac_f32_e32 v60, v122, v63
	v_fmac_f32_e32 v61, v122, v95
	v_fma_f32 v63, -v125, v61, v90
	v_fmac_f32_e32 v91, v125, v60
	v_fmac_f32_e32 v63, v122, v60
	v_fmac_f32_e32 v91, v122, v61
	v_cvt_pk_bf16_f32 v62, v60, v61
	v_cvt_pk_bf16_f32 v60, v63, v91
	ds_write2_b32 v166, v62, v60 offset0:88 offset1:156
	ds_write_b128 v157, v[172:175] offset:256
	v_mfma_f32_16x16x32_bf16 v[172:175], v[4:7], v[48:51], 0
	s_waitcnt lgkmcnt(15)
	v_fma_f32 v60, -v125, v91, v84
	v_fma_f32 v61, v125, v63, v85
	v_fmac_f32_e32 v60, v122, v63
	v_fmac_f32_e32 v61, v122, v91
	v_fma_f32 v63, -v125, v61, v86
	v_fmac_f32_e32 v87, v125, v60
	v_fmac_f32_e32 v63, v122, v60
	v_fmac_f32_e32 v87, v122, v61
	v_cvt_pk_bf16_f32 v62, v60, v61
	v_cvt_pk_bf16_f32 v60, v63, v87
	ds_write2_b32 v165, v62, v60 offset0:96 offset1:164
	ds_write_b128 v157, v[172:175] offset:320
	v_mfma_f32_16x16x32_bf16 v[172:175], v[0:3], v[48:51], 0
	s_waitcnt lgkmcnt(15)
	v_fma_f32 v60, -v125, v87, v80
	v_fma_f32 v61, v125, v63, v81
	v_fmac_f32_e32 v60, v122, v63
	v_fmac_f32_e32 v61, v122, v87
	v_fma_f32 v63, -v125, v61, v82
	v_fmac_f32_e32 v83, v125, v60
	v_fmac_f32_e32 v63, v122, v60
	v_fmac_f32_e32 v83, v122, v61
	v_cvt_pk_bf16_f32 v62, v60, v61
	v_cvt_pk_bf16_f32 v60, v63, v83
	ds_write2_b32 v164, v62, v60 offset0:104 offset1:172
	ds_write_b128 v157, v[172:175] offset:384
	v_mfma_f32_16x16x32_bf16 v[172:175], v[28:31], v[48:51], 0
	s_waitcnt lgkmcnt(15)
	v_fma_f32 v60, -v125, v83, v76
	v_fma_f32 v61, v125, v63, v77
	v_fmac_f32_e32 v60, v122, v63
	v_fmac_f32_e32 v61, v122, v83
	v_fma_f32 v63, -v125, v61, v78
	v_fmac_f32_e32 v79, v125, v60
	v_fmac_f32_e32 v63, v122, v60
	v_fmac_f32_e32 v79, v122, v61
	v_cvt_pk_bf16_f32 v62, v60, v61
	v_cvt_pk_bf16_f32 v60, v63, v79
	ds_write2_b32 v163, v62, v60 offset0:112 offset1:180
	ds_write_b128 v157, v[172:175] offset:448
	s_waitcnt lgkmcnt(15)
	v_fma_f32 v61, -v125, v79, v72
	v_fma_f32 v60, v125, v63, v73
	v_fmac_f32_e32 v61, v122, v63
	v_fmac_f32_e32 v60, v122, v79
	v_pk_fma_f32 v[62:63], v[124:125], v[60:61], v[74:75]
	v_mov_b32_e32 v72, v61
	v_mov_b32_e32 v73, v60
	v_pk_fma_f32 v[130:131], v[122:123], v[72:73], v[62:63]
	v_cvt_pk_bf16_f32 v76, v61, v60
	v_cvt_pk_bf16_f32 v60, v130, v131
	ds_write2_b32 v162, v76, v60 offset0:120 offset1:188
	v_cvt_pk_bf16_f32 v56, v56, v57
	v_cvt_pk_bf16_f32 v57, v58, v59
	v_lshl_add_u64 v[62:63], s[98:99], 0, v[180:181]
	global_store_dwordx2 v[62:63], v[56:57], off
	s_waitcnt vmcnt(1)
	v_mov_b32_e32 v48, v52
	v_mov_b32_e32 v49, v53
	v_mov_b32_e32 v50, v54
	v_mov_b32_e32 v51, v55
	v_lshl_add_u64 v[62:63], s[98:99], 0, v[178:179]
	global_load_dwordx4 v[52:55], v[62:63], off
	s_add_u32 s98, s98, 0x8000
	s_addc_u32 s99, s99, 0
	s_add_i32 s100, s100, 1
	s_cmp_lg_u32 s100, 0x10d
	s_cbranch_scc1 .Ls5f_fwd_loop
	s_waitcnt vmcnt(0)
	s_mov_b32 s23, 0x10d
	s_mov_b32 s24, 0x110d0
	s_add_u32 s0, s56, 0xfc0
	s_addc_u32 s1, s57, 0
	s_branch .LBB0_417
